# v88 + P2 Kg^T record staged through a padded LDS image (Amat region) and copied out with 16-byte stores instead of 16 scattered 2-byte global stores per thread
# baseline (speedup 1.0000x reference)
; #define LAS __attribute__((address_space(3)))
; __device__ __forceinline__ float bflo(unsigned w) { return __uint_as_float(w << 16); }
; __device__ __forceinline__ float bfhi(unsigned w) { return __uint_as_float(w & 0xffff0000u); }
; __device__ __forceinline__ float sum8(float v) { v += dppmov<0xB1>(v); v += dppmov<0x4E>(v); v += dppmov<0x141>(v); return v; }
; __device__ __forceinline__ float silu_fast(float x) { return x * __builtin_amdgcn_rcpf(1.0f + __builtin_amdgcn_exp2f(-1.4426950408889634f * x)); }
; __device__ __forceinline__ void gdn_prep_wg(const bf16* P, const float* SMALL, const float* conv_w, const float* a_log, const float* dt_bias,
;                                             unsigned char* REC, bf16* UF, float* EG, LAS unsigned char* lds, int bh, int n0, int nch) {
;     ...
;                 for (int i = 0; i < 4; ++i) {
;                     if (t - 3 + i >= 0) { const LAS unsigned char* src = raw + (row + i) * RAWP + ten * 256 + c0 * 2; const v4u x0 = *(const LAS v4u*)src, x1 = *(const LAS v4u*)(src + 16);
;                         const float* w = conv_w + (size_t)i * CONVW + pcol;
;                         const f32x4 w0 = *(const f32x4*)w, w1 = *(const f32x4*)(w + 4), w2 = *(const f32x4*)(w + 8), w3 = *(const f32x4*)(w + 12);
;                         acc[0] += w0.x * bflo(x0.x); acc[1] += w0.y * bfhi(x0.x); acc[2] += w0.z * bflo(x0.y); acc[3] += w0.w * bfhi(x0.y);
;                         acc[4] += w1.x * bflo(x0.z); acc[5] += w1.y * bfhi(x0.z); acc[6] += w1.z * bflo(x0.w); acc[7] += w1.w * bfhi(x0.w);
;                         acc[8] += w2.x * bflo(x1.x); acc[9] += w2.y * bfhi(x1.x); acc[10] += w2.z * bflo(x1.y); acc[11] += w2.w * bfhi(x1.y);
;                         acc[12] += w3.x * bflo(x1.z); acc[13] += w3.y * bfhi(x1.z); acc[14] += w3.z * bflo(x1.w); acc[15] += w3.w * bfhi(x1.w); } }
;                 float ss = 0.f;
; #pragma unroll
;                 for (int j = 0; j < 16; ++j) { acc[j] = silu_fast(acc[j]); ss += acc[j] * acc[j]; }
;                 if (ten < 2) { ss = sum8(ss); const float s_ = (1.0f / sqrtf(ss + EPS)) * (ten == 0 ? 0.08838834764831845f : 1.0f);
; #pragma unroll
;                     for (int j = 0; j < 16; ++j) acc[j] *= s_; }
.LBB0_336:
	s_or_b64 exec, exec, s[90:91]
	global_load_dwordx4 v[2:5], v[118:119], off
	global_load_dwordx4 v[10:13], v[118:119], off offset:16
	global_load_dwordx4 v[44:47], v[118:119], off offset:32
	global_load_dwordx4 v[36:39], v[118:119], off offset:48
	ds_read_b128 v[6:9], v201 offset:2608
	ds_read_b128 v[48:51], v201 offset:2624
	v_mul_f32_e32 v19, v18, v19
	v_lshl_add_u64 v[20:21], v[102:103], 0, s[96:97]
	s_waitcnt lgkmcnt(0)
	v_lshlrev_b32_e32 v40, 16, v48
	v_and_b32_e32 v41, 0xffff0000, v48
	v_lshlrev_b32_e32 v32, 16, v51
	v_and_b32_e32 v33, 0xffff0000, v51
	s_waitcnt vmcnt(1)
	v_pk_fma_f32 v[28:29], v[44:45], v[40:41], v[28:29]
	v_lshlrev_b32_e32 v44, 16, v9
	v_and_b32_e32 v45, 0xffff0000, v9
	v_pk_fma_f32 v[12:13], v[12:13], v[44:45], v[24:25]
	v_lshlrev_b32_e32 v44, 16, v8
	v_mul_f32_e32 v9, 0xbfb8aa3b, v12
	v_exp_f32_e32 v9, v9
	v_and_b32_e32 v45, 0xffff0000, v8
	s_waitcnt vmcnt(0)
	v_pk_fma_f32 v[26:27], v[38:39], v[32:33], v[26:27]
	v_lshlrev_b32_e32 v38, 16, v50
	v_add_f32_e32 v9, 1.0, v9
	v_rcp_f32_e32 v24, v9
	v_mul_f32_e32 v9, 0xbfb8aa3b, v13
	v_exp_f32_e32 v9, v9
	v_and_b32_e32 v39, 0xffff0000, v50
	v_pk_fma_f32 v[30:31], v[36:37], v[38:39], v[30:31]
	v_lshlrev_b32_e32 v38, 16, v49
	v_add_f32_e32 v9, 1.0, v9
	v_rcp_f32_e32 v25, v9
	v_pk_fma_f32 v[8:9], v[10:11], v[44:45], v[22:23]
	v_lshlrev_b32_e32 v22, 16, v7
	v_and_b32_e32 v23, 0xffff0000, v7
	v_pk_fma_f32 v[4:5], v[4:5], v[22:23], v[16:17]
	v_lshlrev_b32_e32 v22, 16, v6
	v_mul_f32_e32 v7, 0xbfb8aa3b, v4
	v_exp_f32_e32 v7, v7
	v_and_b32_e32 v23, 0xffff0000, v6
	v_pk_fma_f32 v[2:3], v[2:3], v[22:23], v[14:15]
	v_mul_f32_e32 v10, 0xbfb8aa3b, v8
	v_add_f32_e32 v7, 1.0, v7
	v_rcp_f32_e32 v16, v7
	v_mul_f32_e32 v7, 0xbfb8aa3b, v5
	v_exp_f32_e32 v7, v7
	v_mul_f32_e32 v6, 0xbfb8aa3b, v2
	v_exp_f32_e32 v6, v6
	v_mul_f32_e32 v11, 0xbfb8aa3b, v9
	v_add_f32_e32 v7, 1.0, v7
	v_rcp_f32_e32 v17, v7
	v_mul_f32_e32 v7, 0xbfb8aa3b, v3
	v_exp_f32_e32 v7, v7
	v_exp_f32_e32 v10, v10
	v_exp_f32_e32 v11, v11
	v_add_f32_e32 v6, 1.0, v6
	v_add_f32_e32 v7, 1.0, v7
	v_rcp_f32_e32 v6, v6
	v_rcp_f32_e32 v7, v7
	v_and_b32_e32 v39, 0xffff0000, v49
	v_mul_f32_e32 v40, 0xbfb8aa3b, v28
	v_mul_f32_e32 v41, 0xbfb8aa3b, v29
	v_pk_fma_f32 v[34:35], v[46:47], v[38:39], v[34:35]
	v_exp_f32_e32 v40, v40
	v_exp_f32_e32 v41, v41
	v_add_f32_e32 v10, 1.0, v10
	v_add_f32_e32 v11, 1.0, v11
	v_mul_f32_e32 v38, 0xbfb8aa3b, v34
	v_mul_f32_e32 v39, 0xbfb8aa3b, v35
	v_rcp_f32_e32 v10, v10
	v_rcp_f32_e32 v11, v11
	v_exp_f32_e32 v38, v38
	v_exp_f32_e32 v39, v39
	v_pk_mul_f32 v[6:7], v[2:3], v[6:7]
	v_mul_f32_e32 v36, 0xbfb8aa3b, v30
	v_mul_f32_e32 v37, 0xbfb8aa3b, v31
	v_pk_mul_f32 v[4:5], v[4:5], v[16:17]
	v_pk_mul_f32 v[2:3], v[6:7], v[6:7]
	v_exp_f32_e32 v36, v36
	v_exp_f32_e32 v37, v37
	v_add_f32_e32 v40, 1.0, v40
	v_add_f32_e32 v41, 1.0, v41
	v_pk_mul_f32 v[16:17], v[4:5], v[4:5]
	v_add_f32_e32 v2, v2, v3
	v_mul_f32_e32 v32, 0xbfb8aa3b, v26
	v_mul_f32_e32 v33, 0xbfb8aa3b, v27
	v_rcp_f32_e32 v40, v40
	v_rcp_f32_e32 v41, v41
	v_pk_mul_f32 v[8:9], v[8:9], v[10:11]
	v_add_f32_e32 v2, v16, v2
	v_exp_f32_e32 v32, v32
	v_exp_f32_e32 v33, v33
	v_add_f32_e32 v38, 1.0, v38
	v_add_f32_e32 v39, 1.0, v39
	v_pk_mul_f32 v[10:11], v[8:9], v[8:9]
	v_add_f32_e32 v2, v17, v2
	v_rcp_f32_e32 v38, v38
	v_rcp_f32_e32 v39, v39
	v_pk_mul_f32 v[12:13], v[12:13], v[24:25]
	v_add_f32_e32 v2, v10, v2
	v_add_f32_e32 v36, 1.0, v36
	v_add_f32_e32 v37, 1.0, v37
	v_pk_mul_f32 v[24:25], v[12:13], v[12:13]
	v_add_f32_e32 v2, v11, v2
	v_rcp_f32_e32 v36, v36
	v_rcp_f32_e32 v37, v37
	v_pk_mul_f32 v[28:29], v[28:29], v[40:41]
	v_add_f32_e32 v2, v24, v2
	v_add_f32_e32 v32, 1.0, v32
	v_add_f32_e32 v33, 1.0, v33
	v_pk_mul_f32 v[40:41], v[28:29], v[28:29]
	v_add_f32_e32 v2, v25, v2
	v_rcp_f32_e32 v32, v32
	v_rcp_f32_e32 v33, v33
	v_pk_mul_f32 v[34:35], v[34:35], v[38:39]
	v_add_f32_e32 v2, v40, v2
	v_pk_mul_f32 v[38:39], v[34:35], v[34:35]
	v_add_f32_e32 v2, v41, v2
	v_pk_mul_f32 v[30:31], v[30:31], v[36:37]
	v_add_f32_e32 v2, v38, v2
	v_pk_mul_f32 v[36:37], v[30:31], v[30:31]
	v_add_f32_e32 v2, v39, v2
	v_pk_mul_f32 v[26:27], v[26:27], v[32:33]
	v_add_f32_e32 v2, v36, v2
	v_pk_mul_f32 v[32:33], v[26:27], v[26:27]
	v_add_f32_e32 v2, v37, v2
	v_add_f32_e32 v2, v32, v2
	v_add_f32_e32 v2, v33, v2
	s_nop 1
	v_add_f32_dpp v2, v2, v2 quad_perm:[1,0,3,2] row_mask:0xf bank_mask:0xf bound_ctrl:1
	s_nop 1
	v_add_f32_dpp v2, v2, v2 quad_perm:[2,3,0,1] row_mask:0xf bank_mask:0xf bound_ctrl:1
	s_nop 1
	v_add_f32_dpp v2, v2, v2 row_half_mirror row_mask:0xf bank_mask:0xf bound_ctrl:1
	v_add_f32_e32 v2, 0x358637bd, v2
	v_cmp_gt_f32_e32 vcc, s33, v2
	v_mul_f32_e32 v3, 0x4f800000, v2
	s_nop 0
	v_cndmask_b32_e32 v3, v2, v3, vcc
	v_sqrt_f32_e32 v10, v3
	v_mov_b32_e32 v2, 0
	v_mov_b32_e32 v32, v2
	v_mov_b32_e32 v33, v2
	v_add_u32_e32 v11, -1, v10
	v_fma_f32 v14, -v11, v10, v3
	v_cmp_ge_f32_e64 s[90:91], 0, v14
	v_add_u32_e32 v14, 1, v10
	s_nop 0
	v_cndmask_b32_e64 v11, v10, v11, s[90:91]
	v_fma_f32 v10, -v14, v10, v3
	v_cmp_lt_f32_e64 s[90:91], 0, v10
	s_nop 1
	v_cndmask_b32_e64 v10, v11, v14, s[90:91]
	v_mul_f32_e32 v11, 0x37800000, v10
	v_cndmask_b32_e32 v10, v10, v11, vcc
; #define LAS __attribute__((address_space(3)))
; __device__ __forceinline__ unsigned pk2(float lo, float hi) { const f32x2c v = {lo, hi}; return __builtin_bit_cast(unsigned, __builtin_convertvector(v, bf16x2c)); }
; __device__ __forceinline__ unsigned f2bf(float f) { return pk2(f, f) & 0xffffu; }
; __device__ __forceinline__ void gdn_prep_wg(const bf16* P, const float* SMALL, const float* conv_w, const float* a_log, const float* dt_bias,
;                                             unsigned char* REC, bf16* UF, float* EG, LAS unsigned char* lds, int bh, int n0, int nch) {
;     ...
;                     v4u o0, o1; o0.x = pk2(acc[0], acc[1]); o0.y = pk2(acc[2], acc[3]); o0.z = pk2(acc[4], acc[5]); o0.w = pk2(acc[6], acc[7]);
;                     o1.x = pk2(acc[8], acc[9]); o1.y = pk2(acc[10], acc[11]); o1.z = pk2(acc[12], acc[13]); o1.w = pk2(acc[14], acc[15]);
;                     *(LAS v4u*)(kb + row * 272 + c0 * 2) = o0; *(LAS v4u*)(kb + row * 272 + c0 * 2 + 16) = o1;
;                     const float bg = be * egc; const int off = row & 31, kq = (off & 15) >> 2, kj = (off & 3) + 4 * (off >> 4);
;                     unsigned char* dst = rec + GR_K + ((c0 >> 4) * 2 + (row >> 5)) * 1024 + (16 * kq) * 16 + kj * 2;
; #pragma unroll
;                     for (int e = 0; e < 16; ++e) { *(LAS bf16*)(RT + (128 + c0 + e) * 144 + row * 2) = (bf16)f2bf(acc[e] * bg);
;                         *(bf16*)(dst + e * 16) = (bf16)f2bf(acc[e] * egl); }
	v_cmp_class_f32_e32 vcc, v3, v191
	s_nop 1
	v_cndmask_b32_e32 v3, v10, v3, vcc
	v_div_scale_f32 v10, s[90:91], v3, v3, 1.0
	v_rcp_f32_e32 v11, v10
	s_nop 0
	v_fma_f32 v14, -v10, v11, 1.0
	v_fmac_f32_e32 v11, v14, v11
	v_div_scale_f32 v14, vcc, 1.0, v3, 1.0
	v_mul_f32_e32 v15, v14, v11
	v_fma_f32 v16, -v10, v15, v14
	v_fmac_f32_e32 v15, v16, v11
	v_fma_f32 v10, -v10, v15, v14
	v_div_fmas_f32 v10, v10, v11, v15
	v_div_fixup_f32 v10, v10, v3, 1.0
	v_pk_mul_f32 v[14:15], v[6:7], v[10:11] op_sel_hi:[1,0]
	v_pk_mul_f32 v[16:17], v[4:5], v[10:11] op_sel_hi:[1,0]
	v_pk_mul_f32 v[22:23], v[8:9], v[10:11] op_sel_hi:[1,0]
	v_pk_mul_f32 v[12:13], v[12:13], v[10:11] op_sel_hi:[1,0]
	v_mul_f32_e32 v3, v19, v14
	v_pk_mul_f32 v[24:25], v[28:29], v[10:11] op_sel_hi:[1,0]
	v_pk_mul_f32 v[28:29], v[34:35], v[10:11] op_sel_hi:[1,0]
	v_pk_mul_f32 v[30:31], v[30:31], v[10:11] op_sel_hi:[1,0]
	v_pk_mul_f32 v[26:27], v[26:27], v[10:11] op_sel_hi:[1,0]
	v_cvt_pk_bf16_f32 v4, v14, v15
	v_cvt_pk_bf16_f32 v5, v16, v17
	v_cvt_pk_bf16_f32 v6, v22, v23
	v_cvt_pk_bf16_f32 v7, v12, v13
	v_cvt_pk_bf16_f32 v3, v3, s0
	v_cvt_pk_bf16_f32 v8, v24, v25
	v_cvt_pk_bf16_f32 v9, v28, v29
	v_cvt_pk_bf16_f32 v10, v30, v31
	v_cvt_pk_bf16_f32 v11, v26, v27
	ds_write_b128 v43, v[4:7]
	ds_write_b128 v43, v[8:11] offset:16
	ds_write_b16 v192, v3 offset:53248
	v_and_b32_e32 v236, 7, v0
	v_lshrrev_b32_e32 v237, 3, v0
	v_lshrrev_b32_e32 v238, 5, v237
	v_lshl_add_u32 v238, v236, 1, v238
	v_lshlrev_b32_e32 v235, 4, v238
	v_lshl_add_u32 v239, v238, 10, v235
	v_bfe_u32 v238, v237, 2, 2
	v_lshl_add_u32 v239, v238, 8, v239
	v_and_b32_e32 v238, 3, v237
	v_lshl_add_u32 v239, v238, 1, v239
	v_bfe_u32 v238, v237, 4, 1
	v_lshl_add_u32 v239, v238, 3, v239
	v_add_u32_e32 v239, 0x11800, v239
	v_mul_f32_e32 v3, v42, v14
	v_cvt_pk_bf16_f32 v3, v3, s0
	ds_write_b16 v239, v3
	v_mul_f32_e32 v3, v19, v15
	v_cvt_pk_bf16_f32 v3, v3, s0
	ds_write_b16 v192, v3 offset:53392
	v_mul_f32_e32 v3, v42, v15
	v_cvt_pk_bf16_f32 v3, v3, s0
	ds_write_b16 v239, v3 offset:16
	v_mul_f32_e32 v3, v19, v16
	v_cvt_pk_bf16_f32 v3, v3, s0
	ds_write_b16 v192, v3 offset:53536
	v_mul_f32_e32 v3, v42, v16
	v_cvt_pk_bf16_f32 v3, v3, s0
	ds_write_b16 v239, v3 offset:32
	v_mul_f32_e32 v3, v19, v17
	v_cvt_pk_bf16_f32 v3, v3, s0
	ds_write_b16 v192, v3 offset:53680
	v_mul_f32_e32 v3, v42, v17
	v_cvt_pk_bf16_f32 v3, v3, s0
	ds_write_b16 v239, v3 offset:48
	v_mul_f32_e32 v3, v19, v22
	v_cvt_pk_bf16_f32 v3, v3, s0
	ds_write_b16 v192, v3 offset:53824
	v_mul_f32_e32 v3, v42, v22
	v_cvt_pk_bf16_f32 v3, v3, s0
	ds_write_b16 v239, v3 offset:64
	v_mul_f32_e32 v3, v19, v23
	v_cvt_pk_bf16_f32 v3, v3, s0
	ds_write_b16 v192, v3 offset:53968
	v_mul_f32_e32 v3, v42, v23
	v_cvt_pk_bf16_f32 v3, v3, s0
	ds_write_b16 v239, v3 offset:80
	v_mul_f32_e32 v3, v19, v12
	v_cvt_pk_bf16_f32 v3, v3, s0
	ds_write_b16 v192, v3 offset:54112
	v_mul_f32_e32 v3, v42, v12
	v_cvt_pk_bf16_f32 v3, v3, s0
	ds_write_b16 v239, v3 offset:96
	v_mul_f32_e32 v3, v19, v13
	v_cvt_pk_bf16_f32 v3, v3, s0
	ds_write_b16 v192, v3 offset:54256
	v_mul_f32_e32 v3, v42, v13
	v_cvt_pk_bf16_f32 v3, v3, s0
	ds_write_b16 v239, v3 offset:112
	v_mul_f32_e32 v3, v19, v24
	v_cvt_pk_bf16_f32 v3, v3, s0
	ds_write_b16 v192, v3 offset:54400
	v_mul_f32_e32 v3, v42, v24
	v_cvt_pk_bf16_f32 v3, v3, s0
	ds_write_b16 v239, v3 offset:128
	v_mul_f32_e32 v3, v19, v25
	v_cvt_pk_bf16_f32 v3, v3, s0
	ds_write_b16 v192, v3 offset:54544
	v_mul_f32_e32 v3, v42, v25
	v_cvt_pk_bf16_f32 v3, v3, s0
	ds_write_b16 v239, v3 offset:144
	v_mul_f32_e32 v3, v19, v28
	v_cvt_pk_bf16_f32 v3, v3, s0
	ds_write_b16 v192, v3 offset:54688
	v_mul_f32_e32 v3, v42, v28
	v_cvt_pk_bf16_f32 v3, v3, s0
	ds_write_b16 v239, v3 offset:160
	v_mul_f32_e32 v3, v19, v29
	v_cvt_pk_bf16_f32 v3, v3, s0
	ds_write_b16 v192, v3 offset:54832
	v_mul_f32_e32 v3, v42, v29
	v_cvt_pk_bf16_f32 v3, v3, s0
	ds_write_b16 v239, v3 offset:176
	v_mul_f32_e32 v3, v19, v30
	v_cvt_pk_bf16_f32 v3, v3, s0
	ds_write_b16 v192, v3 offset:54976
	v_mul_f32_e32 v3, v42, v30
	v_cvt_pk_bf16_f32 v3, v3, s0
	ds_write_b16 v239, v3 offset:192
	v_mul_f32_e32 v3, v19, v31
	v_cvt_pk_bf16_f32 v3, v3, s0
	ds_write_b16 v192, v3 offset:55120
	v_mul_f32_e32 v3, v42, v31
	v_cvt_pk_bf16_f32 v3, v3, s0
	ds_write_b16 v239, v3 offset:208
	v_mul_f32_e32 v3, v19, v26
	v_cvt_pk_bf16_f32 v3, v3, s0
	ds_write_b16 v192, v3 offset:55264
	v_mul_f32_e32 v3, v42, v26
	v_cvt_pk_bf16_f32 v3, v3, s0
	ds_write_b16 v239, v3 offset:224
	v_mul_f32_e32 v3, v19, v27
	v_cvt_pk_bf16_f32 v3, v3, s0
	ds_write_b16 v192, v3 offset:55408
	v_mul_f32_e32 v3, v42, v27
	v_cvt_pk_bf16_f32 v3, v3, s0
	ds_write_b16 v239, v3 offset:240
	v_mov_b32_e32 v3, 0
	v_mov_b32_e32 v20, 0
	v_mov_b32_e32 v21, 0
	v_mov_b32_e32 v22, 0
	v_mov_b32_e32 v23, v2
	v_mov_b32_e32 v24, v2
	v_mov_b32_e32 v25, v2
	v_mov_b32_e32 v26, v2
	v_mov_b32_e32 v27, v2
	v_mov_b32_e32 v28, v2
	v_mov_b32_e32 v29, v2
	v_mov_b32_e32 v30, v2
	v_mov_b32_e32 v31, v2
	v_mov_b32_e32 v34, 0
	v_mov_b32_e32 v35, 0
	s_and_saveexec_b64 s[90:91], s[86:87]
	s_cbranch_execnz .LBB0_381
	s_or_b64 exec, exec, s[90:91]
	s_and_saveexec_b64 s[86:87], s[88:89]
	s_cbranch_execnz .LBB0_382

; #define LAS __attribute__((address_space(3)))
; __device__ __forceinline__ unsigned f2bf(float f) { return pk2(f, f) & 0xffffu; }
; #define GBAR() do { asm volatile("s_waitcnt lgkmcnt(0)" ::: "memory"); __builtin_amdgcn_s_barrier(); asm volatile("" ::: "memory"); } while (0)
; __device__ __forceinline__ void gdn_prep_wg(const bf16* P, const float* SMALL, const float* conv_w, const float* a_log, const float* dt_bias,
;                                             unsigned char* REC, bf16* UF, float* EG, LAS unsigned char* lds, int bh, int n0, int nch) {
;     ...
;                     const float bg = be * egc; const int off = row & 31, kq = (off & 15) >> 2, kj = (off & 3) + 4 * (off >> 4);
;                     unsigned char* dst = rec + GR_K + ((c0 >> 4) * 2 + (row >> 5)) * 1024 + (16 * kq) * 16 + kj * 2;
; #pragma unroll
;                     for (int e = 0; e < 16; ++e) { *(LAS bf16*)(RT + (128 + c0 + e) * 144 + row * 2) = (bf16)f2bf(acc[e] * bg);
;                         *(bf16*)(dst + e * 16) = (bf16)f2bf(acc[e] * egl); }
;                 } else {
; #pragma unroll
;                     for (int e = 0; e < 16; ++e) *(LAS bf16*)(RT + (c0 + e) * 144 + row * 2) = (bf16)f2bf(acc[e] * be);
;                 }
;             }
;         }
;         GBAR();
.LBB0_340:
	s_or_b64 exec, exec, s[86:87]
	global_load_dwordx4 v[2:5], v[126:127], off
	global_load_dwordx4 v[10:13], v[126:127], off offset:16
	global_load_dwordx4 v[14:17], v[126:127], off offset:32
	global_load_dwordx4 v[36:39], v[126:127], off offset:48
	ds_read_b128 v[6:9], v201 offset:2864
	ds_read_b128 v[40:43], v201 offset:2880
	s_andn2_b64 vcc, exec, s[24:25]
	s_waitcnt lgkmcnt(0)
	v_and_b32_e32 v19, 0xffff0000, v43
	s_waitcnt vmcnt(0)
	v_fmac_f32_e32 v35, v39, v19
	v_mul_f32_e32 v19, 0xbfb8aa3b, v35
	v_exp_f32_e32 v19, v19
	s_nop 0
	v_add_f32_e32 v19, 1.0, v19
	v_rcp_f32_e32 v19, v19
	s_nop 0
	v_mul_f32_e32 v19, v35, v19
	v_lshlrev_b32_e32 v35, 16, v43
	v_fmac_f32_e32 v34, v38, v35
	v_mul_f32_e32 v35, 0xbfb8aa3b, v34
	v_exp_f32_e32 v35, v35
	s_nop 0
	v_add_f32_e32 v35, 1.0, v35
	v_rcp_f32_e32 v35, v35
	s_nop 0
	v_mul_f32_e32 v34, v34, v35
	v_and_b32_e32 v35, 0xffff0000, v42
	v_fmac_f32_e32 v33, v37, v35
	v_mul_f32_e32 v35, 0xbfb8aa3b, v33
	v_exp_f32_e32 v35, v35
	s_nop 0
	v_add_f32_e32 v35, 1.0, v35
	v_rcp_f32_e32 v35, v35
	s_nop 0
	v_mul_f32_e32 v33, v33, v35
	v_lshlrev_b32_e32 v35, 16, v42
	v_fmac_f32_e32 v32, v36, v35
	v_mul_f32_e32 v35, 0xbfb8aa3b, v32
	v_exp_f32_e32 v35, v35
	s_nop 0
	v_add_f32_e32 v35, 1.0, v35
	v_rcp_f32_e32 v35, v35
	s_nop 0
	v_mul_f32_e32 v32, v32, v35
	v_and_b32_e32 v35, 0xffff0000, v41
	v_fmac_f32_e32 v31, v17, v35
	v_mul_f32_e32 v17, 0xbfb8aa3b, v31
	v_exp_f32_e32 v17, v17
	s_nop 0
	v_add_f32_e32 v17, 1.0, v17
	v_rcp_f32_e32 v17, v17
	s_nop 0
	v_mul_f32_e32 v17, v31, v17
	v_lshlrev_b32_e32 v31, 16, v41
	v_fmac_f32_e32 v30, v16, v31
	v_mul_f32_e32 v16, 0xbfb8aa3b, v30
	v_exp_f32_e32 v16, v16
	s_nop 0
	v_add_f32_e32 v16, 1.0, v16
	v_rcp_f32_e32 v16, v16
	s_nop 0
	v_mul_f32_e32 v16, v30, v16
	v_and_b32_e32 v30, 0xffff0000, v40
	v_fmac_f32_e32 v29, v15, v30
	v_mul_f32_e32 v15, 0xbfb8aa3b, v29
	v_exp_f32_e32 v15, v15
	s_nop 0
	v_add_f32_e32 v15, 1.0, v15
	v_rcp_f32_e32 v15, v15
	s_nop 0
	v_mul_f32_e32 v15, v29, v15
	v_lshlrev_b32_e32 v29, 16, v40
	v_fmac_f32_e32 v28, v14, v29
	v_mul_f32_e32 v14, 0xbfb8aa3b, v28
	v_exp_f32_e32 v14, v14
	s_nop 0
	v_add_f32_e32 v14, 1.0, v14
	v_rcp_f32_e32 v14, v14
	s_nop 0
	v_mul_f32_e32 v14, v28, v14
	v_and_b32_e32 v28, 0xffff0000, v9
	v_lshlrev_b32_e32 v9, 16, v9
	v_fmac_f32_e32 v26, v12, v9
	v_and_b32_e32 v12, 0xffff0000, v8
	v_lshlrev_b32_e32 v8, 16, v8
	v_fmac_f32_e32 v24, v10, v8
	v_and_b32_e32 v10, 0xffff0000, v7
	v_lshlrev_b32_e32 v7, 16, v7
	v_fmac_f32_e32 v22, v4, v7
	v_and_b32_e32 v7, 0xffff0000, v6
	v_lshlrev_b32_e32 v6, 16, v6
	v_fmac_f32_e32 v20, v2, v6
	v_mul_f32_e32 v2, 0xbfb8aa3b, v20
	v_fmac_f32_e32 v21, v3, v7
	v_exp_f32_e32 v2, v2
	v_mul_f32_e32 v3, 0xbfb8aa3b, v21
	v_exp_f32_e32 v3, v3
	v_mul_f32_e32 v4, 0xbfb8aa3b, v22
	v_fmac_f32_e32 v23, v5, v10
	v_exp_f32_e32 v4, v4
	v_add_f32_e32 v2, 1.0, v2
	v_mul_f32_e32 v5, 0xbfb8aa3b, v23
	v_rcp_f32_e32 v2, v2
	v_exp_f32_e32 v5, v5
	v_add_f32_e32 v3, 1.0, v3
	v_mul_f32_e32 v8, 0xbfb8aa3b, v24
	v_rcp_f32_e32 v3, v3
	v_fmac_f32_e32 v25, v11, v12
	v_exp_f32_e32 v8, v8
	v_add_f32_e32 v4, 1.0, v4
	v_mul_f32_e32 v11, 0xbfb8aa3b, v25
	v_rcp_f32_e32 v4, v4
	v_mul_f32_e32 v2, v20, v2
	v_exp_f32_e32 v11, v11
	v_add_f32_e32 v5, 1.0, v5
	v_mul_f32_e32 v2, v18, v2
	v_mul_f32_e32 v9, 0xbfb8aa3b, v26
	v_rcp_f32_e32 v5, v5
	v_mul_f32_e32 v3, v21, v3
	v_cvt_pk_bf16_f32 v2, v2, s0
	v_fmac_f32_e32 v27, v13, v28
	v_exp_f32_e32 v9, v9
	v_add_f32_e32 v8, 1.0, v8
	ds_write_b16 v193, v2 offset:34816
	v_mul_f32_e32 v2, v18, v3
	v_mul_f32_e32 v13, 0xbfb8aa3b, v27
	v_rcp_f32_e32 v8, v8
	v_mul_f32_e32 v4, v22, v4
	v_cvt_pk_bf16_f32 v2, v2, s0
	v_exp_f32_e32 v13, v13
	v_add_f32_e32 v11, 1.0, v11
	ds_write_b16 v193, v2 offset:34960
	v_mul_f32_e32 v2, v18, v4
	v_rcp_f32_e32 v11, v11
	v_mul_f32_e32 v5, v23, v5
	v_cvt_pk_bf16_f32 v2, v2, s0
	v_add_f32_e32 v9, 1.0, v9
	ds_write_b16 v193, v2 offset:35104
	v_mul_f32_e32 v2, v18, v5
	v_rcp_f32_e32 v9, v9
	v_mul_f32_e32 v8, v24, v8
	v_cvt_pk_bf16_f32 v2, v2, s0
	v_add_f32_e32 v13, 1.0, v13
	ds_write_b16 v193, v2 offset:35248
	v_mul_f32_e32 v2, v18, v8
	v_rcp_f32_e32 v13, v13
	v_mul_f32_e32 v11, v25, v11
	v_cvt_pk_bf16_f32 v2, v2, s0
	ds_write_b16 v193, v2 offset:35392
	v_mul_f32_e32 v2, v18, v11
	v_mul_f32_e32 v9, v26, v9
	v_cvt_pk_bf16_f32 v2, v2, s0
	ds_write_b16 v193, v2 offset:35536
	v_mul_f32_e32 v2, v18, v9
	v_mul_f32_e32 v13, v27, v13
	v_cvt_pk_bf16_f32 v2, v2, s0
	ds_write_b16 v193, v2 offset:35680
	v_mul_f32_e32 v2, v18, v13
	v_cvt_pk_bf16_f32 v2, v2, s0
	ds_write_b16 v193, v2 offset:35824
	v_mul_f32_e32 v2, v18, v14
	v_cvt_pk_bf16_f32 v2, v2, s0
	ds_write_b16 v193, v2 offset:35968
	v_mul_f32_e32 v2, v18, v15
	v_cvt_pk_bf16_f32 v2, v2, s0
	ds_write_b16 v193, v2 offset:36112
	v_mul_f32_e32 v2, v18, v16
	v_cvt_pk_bf16_f32 v2, v2, s0
	ds_write_b16 v193, v2 offset:36256
	v_mul_f32_e32 v2, v18, v17
	v_cvt_pk_bf16_f32 v2, v2, s0
	ds_write_b16 v193, v2 offset:36400
	v_mul_f32_e32 v2, v18, v32
	v_cvt_pk_bf16_f32 v2, v2, s0
	ds_write_b16 v193, v2 offset:36544
	v_mul_f32_e32 v2, v18, v33
	v_cvt_pk_bf16_f32 v2, v2, s0
	ds_write_b16 v193, v2 offset:36688
	v_mul_f32_e32 v2, v18, v34
	v_cvt_pk_bf16_f32 v2, v2, s0
	ds_write_b16 v193, v2 offset:36832
	v_mul_f32_e32 v2, v18, v19
	v_cvt_pk_bf16_f32 v2, v2, s0
	ds_write_b16 v193, v2 offset:36976
	s_waitcnt lgkmcnt(0)
	s_barrier
	v_lshlrev_b32_e32 v240, 4, v0
	v_lshrrev_b32_e32 v242, 6, v0
	v_lshl_add_u32 v241, v242, 4, v240
	v_add_u32_e32 v241, 0x11800, v241
	ds_read_b128 v[244:247], v241
	ds_read_b128 v[248:251], v241 offset:8320
	v_add_u32_e32 v242, 0x11780, v240
	v_sub_u32_e32 v242, v242, v239
	v_add_u32_e32 v242, v242, v235
	v_ashrrev_i32_e32 v243, 31, v242
	v_lshl_add_u64 v[236:237], v[102:103], 0, v[242:243]
	v_lshl_add_u64 v[236:237], v[236:237], 0, s[96:97]
	v_add_u32_e32 v242, 0x2000, v242
	v_ashrrev_i32_e32 v243, 31, v242
	v_lshl_add_u64 v[252:253], v[102:103], 0, v[242:243]
	v_lshl_add_u64 v[252:253], v[252:253], 0, s[96:97]
	s_waitcnt lgkmcnt(0)
	s_barrier
	global_store_dwordx4 v[236:237], v[244:247], off
	global_store_dwordx4 v[252:253], v[248:251], off
	s_cbranch_vccnz .LBB0_355
	v_readlane_b32 s16, v255, 39
	v_readlane_b32 s17, v255, 40
	s_andn2_b64 vcc, exec, s[16:17]
	s_cbranch_vccnz .LBB0_343
	v_readlane_b32 s16, v254, 41
	v_readlane_b32 s20, v254, 45
	v_readlane_b32 s21, v254, 46
	s_add_i32 s24, s26, 0
	s_add_i32 m0, s24, 0x16000
	v_lshl_add_u64 v[2:3], s[20:21], 0, v[128:129]
	global_load_lds_dwordx4 v[2:3], off
	v_readlane_b32 s17, v254, 42
	v_readlane_b32 s18, v254, 43
	v_readlane_b32 s19, v254, 44
	v_readlane_b32 s22, v254, 47
	v_readlane_b32 s23, v254, 48
